# attention O rescale: scalar v_mul_f32 pairs instead of packed v_pk_mul_f32 beside the MFMAs
# baseline (speedup 1.0000x reference)
; #define MFMA32(a, b, c) __builtin_amdgcn_mfma_f32_32x32x16_bf16((a), (b), (c), 0, 0, 0)
;     ...
;   for (int kt = 0; kt < nkt; ++kt) {
;     __syncthreads();
; #pragma unroll
;     for (int i = 0; i < 3; ++i) {
;       int c = tid + 256 * i, key = c / 12, part = c % 12;
;       *(u32x4*)(Ks + key * 104 + part * 8) = rk[i];
;     }
; #pragma unroll
;     for (int i = 0; i < 2; ++i) {
;       int c = tid + 256 * i, dv = c >> 3, part = c & 7;
;       *(u32x2*)(Vs + dv * 68 + part * 8) = mk2(rv[i].x, rv[i].y);
;       *(u32x2*)(Vs + dv * 68 + part * 8 + 4) = mk2(rv[i].z, rv[i].w);
;     }
;     __syncthreads();
;     if (kt + 1 < nkt) loadt(kt + 1);
;     f32x16 S[2][2];
; #pragma unroll
;     for (int g = 0; g < 2; ++g) { zero_acc(S[g][0]); zero_acc(S[g][1]); }
; #pragma unroll
;     for (int mt = 0; mt < 2; ++mt)
; #pragma unroll
;       for (int s = 0; s < 6; ++s) {
;         const bf16x8 a = *(const bf16x8*)(Ks + (mt * 32 + l31) * 104 + s * 16 + hh * 8);
;         S[0][mt] = MFMA32(a, qf[0][s], S[0][mt]);
;         S[1][mt] = MFMA32(a, qf[1][s], S[1][mt]);
;       }
;     asm volatile("s_nop 15\n\ts_nop 15" ::: "memory");
; #pragma unroll
;     for (int g = 0; g < 2; ++g) {
;       float mx = -1e30f;
; #pragma unroll
;       for (int mt = 0; mt < 2; ++mt)
; #pragma unroll
;         for (int r = 0; r < 16; ++r) mx = fmaxf(mx, S[g][mt][r]);
;       mx = fmaxf(mx, __shfl_xor(mx, 32)) * scl;
;       const float mnew = fmaxf(mrun[g], mx);
;       const float alpha = __builtin_amdgcn_exp2f(mrun[g] - mnew);
;       mrun[g] = mnew;
;       float ps = 0.f;
; #pragma unroll
;       for (int mt = 0; mt < 2; ++mt)
; #pragma unroll
;         for (int r = 0; r < 16; ++r) { float e = __builtin_amdgcn_exp2f(fmaf(S[g][mt][r], scl, -mnew)); S[g][mt][r] = e; ps += e; }
;       lsum[g] = lsum[g] * alpha + ps;
;       if (__builtin_amdgcn_ballot_w64(alpha != 1.f) != 0ull) {
; #pragma unroll
;         for (int d = 0; d < 2; ++d)
; #pragma unroll
;           for (int r = 0; r < 16; ++r) O[g][d][r] *= alpha;
;       }
.Latt_kt:
	v_lshl_add_u64 v[220:221], s[8:9], 0, v[212:213]
	s_barrier
	s_waitcnt vmcnt(4)
	ds_write_b128 v239, v[178:181]
	s_waitcnt vmcnt(3)
	ds_write_b128 v240, v[182:185]
	s_waitcnt vmcnt(2)
	ds_write_b128 v241, v[186:189]
	s_waitcnt vmcnt(1)
	ds_write2_b64 v242, v[190:191], v[192:193] offset1:1
	s_waitcnt vmcnt(0)
	ds_write2_b64 v243, v[194:195], v[196:197] offset1:1
	s_waitcnt lgkmcnt(0)
	s_barrier
	global_load_dwordx4 v[178:181], v[220:221], off
	v_lshl_add_u64 v[220:221], s[8:9], 0, v[210:211]
	global_load_dwordx4 v[182:185], v[220:221], off
	v_lshl_add_u64 v[220:221], s[8:9], 0, v[208:209]
	global_load_dwordx4 v[186:189], v[220:221], off
	v_lshl_add_u64 v[220:221], s[8:9], 0, v[206:207]
	global_load_dwordx4 v[190:193], v[220:221], off
	v_lshl_add_u64 v[220:221], s[8:9], 0, v[204:205]
	global_load_dwordx4 v[194:197], v[220:221], off
	ds_read_b128 v[220:223], v238
	ds_read_b128 v[224:227], v238 offset:6656
	ds_read_b128 v[230:233], v238 offset:32
	s_waitcnt lgkmcnt(2)
	v_mfma_f32_32x32x16_bf16 v[66:81], v[220:223], v[170:173], 0
	ds_read_b128 v[220:223], v238 offset:6688
	s_waitcnt lgkmcnt(2)
	v_mfma_f32_32x32x16_bf16 v[82:97], v[224:227], v[170:173], 0
	ds_read_b128 v[224:227], v238 offset:64
	s_waitcnt lgkmcnt(2)
	v_mfma_f32_32x32x16_bf16 v[66:81], v[230:233], v[158:161], v[66:81]
	ds_read_b128 v[230:233], v238 offset:6720
	s_waitcnt lgkmcnt(2)
	v_mfma_f32_32x32x16_bf16 v[82:97], v[220:223], v[158:161], v[82:97]
	ds_read_b128 v[220:223], v238 offset:96
	s_waitcnt lgkmcnt(2)
	v_mfma_f32_32x32x16_bf16 v[66:81], v[224:227], v[154:157], v[66:81]
	ds_read_b128 v[224:227], v238 offset:6752
	s_waitcnt lgkmcnt(2)
	v_mfma_f32_32x32x16_bf16 v[82:97], v[230:233], v[154:157], v[82:97]
	ds_read_b128 v[230:233], v238 offset:128
	s_waitcnt lgkmcnt(2)
	v_mfma_f32_32x32x16_bf16 v[66:81], v[220:223], v[142:145], v[66:81]
	ds_read_b128 v[220:223], v238 offset:6784
	s_waitcnt lgkmcnt(2)
	v_mfma_f32_32x32x16_bf16 v[82:97], v[224:227], v[142:145], v[82:97]
	ds_read_b128 v[224:227], v238 offset:160
	s_waitcnt lgkmcnt(2)
	v_mfma_f32_32x32x16_bf16 v[66:81], v[230:233], v[138:141], v[66:81]
	ds_read_b128 v[230:233], v238 offset:6816
	s_waitcnt lgkmcnt(2)
	v_mfma_f32_32x32x16_bf16 v[82:97], v[220:223], v[138:141], v[82:97]
	s_waitcnt lgkmcnt(1)
	v_mfma_f32_32x32x16_bf16 v[66:81], v[224:227], v[130:133], v[66:81]
	s_waitcnt lgkmcnt(0)
	v_mfma_f32_32x32x16_bf16 v[82:97], v[230:233], v[130:133], v[82:97]
	ds_read_b128 v[220:223], v238
	ds_read_b128 v[224:227], v238 offset:6656
	ds_read_b128 v[230:233], v238 offset:32
	s_waitcnt lgkmcnt(2)
	v_mfma_f32_32x32x16_bf16 v[98:113], v[220:223], v[174:177], 0
	ds_read_b128 v[220:223], v238 offset:6688
	s_waitcnt lgkmcnt(2)
	v_mfma_f32_32x32x16_bf16 v[114:129], v[224:227], v[174:177], 0
	s_nop 7
	v_max3_f32 v251, v66, s63, v67
	v_max3_f32 v254, v68, s63, v69
	v_max3_f32 v251, v251, v70, v71
	v_max3_f32 v254, v254, v72, v73
	v_max3_f32 v251, v251, v74, v75
	v_max3_f32 v254, v254, v76, v77
	v_max3_f32 v251, v251, v78, v79
	v_max3_f32 v254, v254, v80, v81
	v_max3_f32 v251, v251, v82, v83
	v_max3_f32 v254, v254, v84, v85
	v_max3_f32 v251, v251, v86, v87
	v_max3_f32 v254, v254, v88, v89
	v_max3_f32 v251, v251, v90, v91
	ds_read_b128 v[224:227], v238 offset:64
	s_waitcnt lgkmcnt(2)
	v_mfma_f32_32x32x16_bf16 v[98:113], v[230:233], v[166:169], v[98:113]
	v_max3_f32 v254, v254, v92, v93
	v_max3_f32 v251, v251, v94, v95
	v_max3_f32 v254, v254, v96, v97
	v_max_f32_e32 v251, v251, v254
	v_mov_b32_e32 v254, v251
	s_nop 1
	v_permlane32_swap_b32_e32 v254, v251
	v_max_f32_e32 v251, v251, v254
	v_mul_f32_e32 v251, 0x3e16c740, v251
	v_max_f32_e32 v254, v246, v246
	v_max_f32_e32 v251, v254, v251
	v_sub_f32_e32 v236, v246, v251
	v_exp_f32_e32 v236, v236
	v_mov_b32_e32 v246, v251
	v_cmp_neq_f32_e32 vcc, 1.0, v236
	s_cbranch_vccz .Latt_noscale0
	v_mul_f32_e32 v50, v236, v50
	v_mul_f32_e32 v51, v236, v51
	v_mul_f32_e32 v52, v236, v52
	v_mul_f32_e32 v53, v236, v53
	v_mul_f32_e32 v54, v236, v54
	v_mul_f32_e32 v55, v236, v55
	v_mul_f32_e32 v56, v236, v56
	v_mul_f32_e32 v57, v236, v57
	v_mul_f32_e32 v58, v236, v58
	v_mul_f32_e32 v59, v236, v59
	v_mul_f32_e32 v60, v236, v60
	v_mul_f32_e32 v61, v236, v61
	v_mul_f32_e32 v62, v236, v62
	v_mul_f32_e32 v63, v236, v63
	v_mul_f32_e32 v64, v236, v64
	v_mul_f32_e32 v65, v236, v65
	v_mul_f32_e32 v34, v236, v34
	v_mul_f32_e32 v35, v236, v35
	v_mul_f32_e32 v36, v236, v36
	v_mul_f32_e32 v37, v236, v37
	v_mul_f32_e32 v38, v236, v38
	v_mul_f32_e32 v39, v236, v39
	v_mul_f32_e32 v40, v236, v40
	v_mul_f32_e32 v41, v236, v41
	v_mul_f32_e32 v42, v236, v42
	v_mul_f32_e32 v43, v236, v43
	v_mul_f32_e32 v44, v236, v44
	v_mul_f32_e32 v45, v236, v45
	v_mul_f32_e32 v46, v236, v46
	v_mul_f32_e32 v47, v236, v47
	v_mul_f32_e32 v48, v236, v48
	v_mul_f32_e32 v49, v236, v49
; #define MFMA32(a, b, c) __builtin_amdgcn_mfma_f32_32x32x16_bf16((a), (b), (c), 0, 0, 0)
; DI unsigned pack2(float lo, float hi) { f32x2 v; v.x = lo; v.y = hi; return __builtin_bit_cast(unsigned, __builtin_convertvector(v, hwbf2)); }
;     ...
;     for (int g = 0; g < 2; ++g) {
;       float mx = -1e30f;
; #pragma unroll
;       for (int mt = 0; mt < 2; ++mt)
; #pragma unroll
;         for (int r = 0; r < 16; ++r) mx = fmaxf(mx, S[g][mt][r]);
;       mx = fmaxf(mx, __shfl_xor(mx, 32)) * scl;
;       const float mnew = fmaxf(mrun[g], mx);
;       const float alpha = __builtin_amdgcn_exp2f(mrun[g] - mnew);
;       mrun[g] = mnew;
;       float ps = 0.f;
; #pragma unroll
;       for (int mt = 0; mt < 2; ++mt)
; #pragma unroll
;         for (int r = 0; r < 16; ++r) { float e = __builtin_amdgcn_exp2f(fmaf(S[g][mt][r], scl, -mnew)); S[g][mt][r] = e; ps += e; }
;       lsum[g] = lsum[g] * alpha + ps;
;       if (__builtin_amdgcn_ballot_w64(alpha != 1.f) != 0ull) {
; #pragma unroll
;         for (int d = 0; d < 2; ++d)
; #pragma unroll
;           for (int r = 0; r < 16; ++r) O[g][d][r] *= alpha;
;       }
;     }
; #pragma unroll
;     for (int mt = 0; mt < 2; ++mt)
; #pragma unroll
;       for (int s2 = 0; s2 < 2; ++s2) {
;         bf16x8 pf[2];
; #pragma unroll
;         for (int g = 0; g < 2; ++g) {
;           unsigned pk[4];
; #pragma unroll
;           for (int q = 0; q < 4; ++q) pk[q] = pack2(S[g][mt][8 * s2 + 2 * q], S[g][mt][8 * s2 + 2 * q + 1]);
;           pf[g] = __builtin_bit_cast(bf16x8, (u32x4{pk[0], pk[1], pk[2], pk[3]}));
;         }
; #pragma unroll
;         for (int d = 0; d < 2; ++d) {
;           const u16* vp = Vs + (d * 32 + l31) * 68 + mt * 32 + s2 * 16 + 4 * hh;
;           u32x2 lo = *(const u32x2*)vp, hi = *(const u32x2*)(vp + 8);
;           const bf16x8 va = __builtin_bit_cast(bf16x8, (u32x4{lo.x, lo.y, hi.x, hi.y}));
;           O[0][d] = MFMA32(va, pf[0], O[0][d]);
;           O[1][d] = MFMA32(va, pf[1], O[1][d]);
;         }
;       }
.Latt_noscale0:
	v_fma_f32 v66, v66, s56, -v251
	v_fma_f32 v67, v67, s56, -v251
	ds_read_b128 v[230:233], v238 offset:6720
	s_waitcnt lgkmcnt(2)
	v_mfma_f32_32x32x16_bf16 v[114:129], v[220:223], v[166:169], v[114:129]
	v_exp_f32_e32 v66, v66
	v_exp_f32_e32 v67, v67
	v_fma_f32 v68, v68, s56, -v251
	v_add_f32_e32 v254, 0, v66
	v_fma_f32 v69, v69, s56, -v251
	v_add_f32_e32 v254, v67, v254
	v_exp_f32_e32 v68, v68
	v_exp_f32_e32 v69, v69
	v_fma_f32 v70, v70, s56, -v251
	v_add_f32_e32 v254, v68, v254
	v_fma_f32 v71, v71, s56, -v251
	v_add_f32_e32 v254, v69, v254
	v_exp_f32_e32 v70, v70
	v_exp_f32_e32 v71, v71
	ds_read_b128 v[220:223], v238 offset:96
	s_waitcnt lgkmcnt(2)
	v_mfma_f32_32x32x16_bf16 v[98:113], v[224:227], v[162:165], v[98:113]
	v_fma_f32 v72, v72, s56, -v251
	v_add_f32_e32 v254, v70, v254
	v_fma_f32 v73, v73, s56, -v251
	v_add_f32_e32 v254, v71, v254
	v_exp_f32_e32 v72, v72
	v_exp_f32_e32 v73, v73
	v_fma_f32 v74, v74, s56, -v251
	v_add_f32_e32 v254, v72, v254
	v_fma_f32 v75, v75, s56, -v251
	v_add_f32_e32 v254, v73, v254
	v_exp_f32_e32 v74, v74
	v_exp_f32_e32 v75, v75
	v_fma_f32 v76, v76, s56, -v251
	v_add_f32_e32 v254, v74, v254
	ds_read_b128 v[224:227], v238 offset:6752
	s_waitcnt lgkmcnt(2)
	v_mfma_f32_32x32x16_bf16 v[114:129], v[230:233], v[162:165], v[114:129]
	v_fma_f32 v77, v77, s56, -v251
	v_add_f32_e32 v254, v75, v254
	v_exp_f32_e32 v76, v76
	v_exp_f32_e32 v77, v77
	v_fma_f32 v78, v78, s56, -v251
	v_add_f32_e32 v254, v76, v254
	v_fma_f32 v79, v79, s56, -v251
	v_add_f32_e32 v254, v77, v254
	v_exp_f32_e32 v78, v78
	v_exp_f32_e32 v79, v79
	v_fma_f32 v80, v80, s56, -v251
	v_add_f32_e32 v254, v78, v254
	v_fma_f32 v81, v81, s56, -v251
	v_add_f32_e32 v254, v79, v254
	ds_read_b128 v[230:233], v238 offset:128
	s_waitcnt lgkmcnt(2)
	v_mfma_f32_32x32x16_bf16 v[98:113], v[220:223], v[150:153], v[98:113]
	v_exp_f32_e32 v80, v80
	v_exp_f32_e32 v81, v81
	v_fma_f32 v82, v82, s56, -v251
	v_add_f32_e32 v254, v80, v254
	v_fma_f32 v83, v83, s56, -v251
	v_add_f32_e32 v254, v81, v254
	v_exp_f32_e32 v82, v82
	v_exp_f32_e32 v83, v83
	v_fma_f32 v84, v84, s56, -v251
	v_add_f32_e32 v254, v82, v254
	v_fma_f32 v85, v85, s56, -v251
	v_add_f32_e32 v254, v83, v254
	v_exp_f32_e32 v84, v84
	v_exp_f32_e32 v85, v85
	ds_read_b128 v[220:223], v238 offset:6784
	s_waitcnt lgkmcnt(2)
	v_mfma_f32_32x32x16_bf16 v[114:129], v[224:227], v[150:153], v[114:129]
	v_fma_f32 v86, v86, s56, -v251
	v_add_f32_e32 v254, v84, v254
	v_fma_f32 v87, v87, s56, -v251
	v_add_f32_e32 v254, v85, v254
	v_exp_f32_e32 v86, v86
	v_exp_f32_e32 v87, v87
	v_fma_f32 v88, v88, s56, -v251
	v_add_f32_e32 v254, v86, v254
	v_fma_f32 v89, v89, s56, -v251
	v_add_f32_e32 v254, v87, v254
	v_exp_f32_e32 v88, v88
	v_exp_f32_e32 v89, v89
	v_fma_f32 v90, v90, s56, -v251
	v_add_f32_e32 v254, v88, v254
	ds_read_b128 v[224:227], v238 offset:160
	s_waitcnt lgkmcnt(2)
	v_mfma_f32_32x32x16_bf16 v[98:113], v[230:233], v[146:149], v[98:113]
	v_fma_f32 v91, v91, s56, -v251
	v_add_f32_e32 v254, v89, v254
	v_exp_f32_e32 v90, v90
	v_exp_f32_e32 v91, v91
	v_fma_f32 v92, v92, s56, -v251
	v_add_f32_e32 v254, v90, v254
	v_fma_f32 v93, v93, s56, -v251
	v_add_f32_e32 v254, v91, v254
	v_exp_f32_e32 v92, v92
	v_exp_f32_e32 v93, v93
	v_fma_f32 v94, v94, s56, -v251
	v_add_f32_e32 v254, v92, v254
	v_fma_f32 v95, v95, s56, -v251
	v_add_f32_e32 v254, v93, v254
	ds_read_b128 v[230:233], v238 offset:6816
	s_waitcnt lgkmcnt(2)
	v_mfma_f32_32x32x16_bf16 v[114:129], v[220:223], v[146:149], v[114:129]
	v_exp_f32_e32 v94, v94
	v_exp_f32_e32 v95, v95
	v_fma_f32 v96, v96, s56, -v251
	v_add_f32_e32 v254, v94, v254
	v_fma_f32 v97, v97, s56, -v251
	v_add_f32_e32 v254, v95, v254
	v_exp_f32_e32 v96, v96
	v_exp_f32_e32 v97, v97
	v_add_f32_e32 v254, v96, v254
	v_add_f32_e32 v254, v97, v254
	v_fmac_f32_e32 v254, v247, v236
	v_mov_b32_e32 v247, v254
	v_cvt_pk_bf16_f32 v66, v66, v67
	v_cvt_pk_bf16_f32 v67, v68, v69
	s_waitcnt lgkmcnt(1)
	v_mfma_f32_32x32x16_bf16 v[98:113], v[224:227], v[134:137], v[98:113]
	v_cvt_pk_bf16_f32 v68, v70, v71
	v_cvt_pk_bf16_f32 v69, v72, v73
	v_cvt_pk_bf16_f32 v70, v74, v75
	v_cvt_pk_bf16_f32 v71, v76, v77
	v_cvt_pk_bf16_f32 v72, v78, v79
	v_cvt_pk_bf16_f32 v73, v80, v81
	v_cvt_pk_bf16_f32 v74, v82, v83
	v_cvt_pk_bf16_f32 v75, v84, v85
	v_cvt_pk_bf16_f32 v76, v86, v87
	v_cvt_pk_bf16_f32 v77, v88, v89
	v_cvt_pk_bf16_f32 v78, v90, v91
	v_cvt_pk_bf16_f32 v79, v92, v93
	v_cvt_pk_bf16_f32 v80, v94, v95
	v_cvt_pk_bf16_f32 v81, v96, v97
	s_waitcnt lgkmcnt(0)
	v_mfma_f32_32x32x16_bf16 v[114:129], v[230:233], v[134:137], v[114:129]
	ds_read2_b64 v[220:223], v214 offset0:128 offset1:130
	ds_read2_b64 v[224:227], v216 offset0:128 offset1:130
	ds_read2_b64 v[230:233], v214 offset0:132 offset1:134
	s_waitcnt lgkmcnt(2)
	v_mfma_f32_32x32x16_bf16 v[50:65], v[220:223], v[66:69], v[50:65]
	s_nop 9
	v_max3_f32 v251, v98, s63, v99
	v_max3_f32 v254, v100, s63, v101
	v_max3_f32 v251, v251, v102, v103
	v_max3_f32 v254, v254, v104, v105
	v_max3_f32 v251, v251, v106, v107
	v_max3_f32 v254, v254, v108, v109
	v_max3_f32 v251, v251, v110, v111
	v_max3_f32 v254, v254, v112, v113
	v_max3_f32 v251, v251, v114, v115
	v_max3_f32 v254, v254, v116, v117
	v_max3_f32 v251, v251, v118, v119
	v_max3_f32 v254, v254, v120, v121
	v_max3_f32 v251, v251, v122, v123
	v_max3_f32 v254, v254, v124, v125
	v_max3_f32 v251, v251, v126, v127
	v_max3_f32 v254, v254, v128, v129
	v_max_f32_e32 v251, v251, v254
	v_mov_b32_e32 v254, v251
	s_nop 1
	v_permlane32_swap_b32_e32 v254, v251
	v_max_f32_e32 v251, v251, v254
	v_mul_f32_e32 v251, 0x3e16c740, v251
	v_max_f32_e32 v254, v249, v249
	ds_read2_b64 v[220:223], v216 offset0:132 offset1:134
	s_waitcnt lgkmcnt(2)
	v_mfma_f32_32x32x16_bf16 v[34:49], v[224:227], v[66:69], v[34:49]
	v_max_f32_e32 v251, v254, v251
	v_sub_f32_e32 v250, v249, v251
	v_exp_f32_e32 v250, v250
	v_mov_b32_e32 v249, v251
	v_cmp_neq_f32_e32 vcc, 1.0, v250
	s_cbranch_vccz .Latt_noscale1
	v_mul_f32_e32 v18, v250, v18
	v_mul_f32_e32 v19, v250, v19
	v_mul_f32_e32 v20, v250, v20
	v_mul_f32_e32 v21, v250, v21
	v_mul_f32_e32 v22, v250, v22
	v_mul_f32_e32 v23, v250, v23
	v_mul_f32_e32 v24, v250, v24
	v_mul_f32_e32 v25, v250, v25
	v_mul_f32_e32 v26, v250, v26
	v_mul_f32_e32 v27, v250, v27
	v_mul_f32_e32 v28, v250, v28
	v_mul_f32_e32 v29, v250, v29
	v_mul_f32_e32 v30, v250, v30
	v_mul_f32_e32 v31, v250, v31
	v_mul_f32_e32 v32, v250, v32
	v_mul_f32_e32 v33, v250, v33
	v_mul_f32_e32 v2, v250, v2
	v_mul_f32_e32 v3, v250, v3
	v_mul_f32_e32 v4, v250, v4
	v_mul_f32_e32 v5, v250, v5
	v_mul_f32_e32 v6, v250, v6
	v_mul_f32_e32 v7, v250, v7
	v_mul_f32_e32 v8, v250, v8
	v_mul_f32_e32 v9, v250, v9
	v_mul_f32_e32 v10, v250, v10
	v_mul_f32_e32 v11, v250, v11
	v_mul_f32_e32 v12, v250, v12
	v_mul_f32_e32 v13, v250, v13
	v_mul_f32_e32 v14, v250, v14
	v_mul_f32_e32 v15, v250, v15
	v_mul_f32_e32 v16, v250, v16
	v_mul_f32_e32 v17, v250, v17
